# GEMM unit loops: the 128 accumulator registers cleared as 64 aligned pairs with v_mov_b64 instead of 128 v_mov_b32 per unit
# speedup vs baseline: 1.0033x; 1.0033x over previous
;     __device__ __forceinline__ bool next(int i, pg8::Unit& u) const { const int L = i * G + c; if (L >= NG * 8) return false; u.pm = (L >> 3) * 9 + (L & 7); u.pn = L >> 3; return true; }
; template <class Epi, class Sched, bool ALIGN_EPI = false, bool SP2 = false>
; __device__ __forceinline__ void gemm_phase(PG8_LAS unsigned char* lds, const Gemm g, const Sched& S, const Epi& E) {
;     ...
;         const bool has_next = S.next(ui + 1, nxt);
;         const char* nA = has_next ? (const char*)g.A + (size_t)nxt.pm * tstepA : cA; const char* nB = has_next ? (const char*)g.Bt + (size_t)nxt.pn * tstepB : cB;
;     ...
; #pragma unroll
;         for (int a = 0; a < 2; ++a)
; #pragma unroll
;             for (int b = 0; b < 2; ++b)
; #pragma unroll
;                 for (int m = 0; m < 4; ++m)
; #pragma unroll
;                     for (int n = 0; n < 2; ++n) acc[a][b][m][n] = (f32x4){0.f, 0.f, 0.f, 0.f};
;         cur = nxt; cA = nA; cB = nB; ++ui;
.LBB0_196:
	s_ashr_i32 s41, s40, 31
	s_lshl_b64 s[6:7], s[40:41], 19
	s_add_u32 s42, s31, s6
	s_addc_u32 s43, s52, s7
	s_and_b64 s[6:7], s[4:5], exec
	s_cselect_b32 s11, s43, s49
	s_cselect_b32 s13, s42, s48
	s_ashr_i32 s37, s36, 31
	s_lshl_b64 s[6:7], s[36:37], 19
	s_add_u32 s44, s53, s6
	s_addc_u32 s45, s54, s7
	s_and_b64 s[6:7], s[4:5], exec
	s_cselect_b32 s33, s45, s47
	s_cselect_b32 s37, s44, s46
	s_add_u32 s6, s48, 0x40080
	s_addc_u32 s7, s49, 0
	s_add_u32 s38, s46, 0x100
	v_mov_b32_e32 v2, 0
	s_addc_u32 s39, s47, 0
	s_mov_b32 s41, -2
	v_mov_b32_e32 v3, v2
	v_mov_b64_e32 v[4:5], v[2:3]
	v_mov_b64_e32 v[6:7], v[2:3]
	v_mov_b64_e32 v[8:9], v[2:3]
	v_mov_b64_e32 v[10:11], v[2:3]
	v_mov_b64_e32 v[12:13], v[2:3]
	v_mov_b64_e32 v[14:15], v[2:3]
	v_mov_b64_e32 v[16:17], v[2:3]
	v_mov_b64_e32 v[18:19], v[2:3]
	v_mov_b64_e32 v[20:21], v[2:3]
	v_mov_b64_e32 v[22:23], v[2:3]
	s_waitcnt vmcnt(0)
	v_mov_b64_e32 v[24:25], v[2:3]
	v_mov_b64_e32 v[26:27], v[2:3]
	v_mov_b64_e32 v[28:29], v[2:3]
	v_mov_b64_e32 v[30:31], v[2:3]
	v_mov_b64_e32 v[32:33], v[2:3]
	v_mov_b64_e32 v[34:35], v[2:3]
	v_mov_b64_e32 v[36:37], v[2:3]
	v_mov_b64_e32 v[38:39], v[2:3]
	v_mov_b64_e32 v[40:41], v[2:3]
	v_mov_b64_e32 v[42:43], v[2:3]
	v_mov_b64_e32 v[44:45], v[2:3]
	v_mov_b64_e32 v[46:47], v[2:3]
	v_mov_b64_e32 v[48:49], v[2:3]
	v_mov_b64_e32 v[50:51], v[2:3]
	v_mov_b64_e32 v[52:53], v[2:3]
	v_mov_b64_e32 v[54:55], v[2:3]
	v_mov_b64_e32 v[56:57], v[2:3]
	v_mov_b64_e32 v[58:59], v[2:3]
	v_mov_b64_e32 v[60:61], v[2:3]
	v_mov_b64_e32 v[62:63], v[2:3]
	v_mov_b64_e32 v[64:65], v[2:3]
	v_mov_b64_e32 v[66:67], v[2:3]
	v_mov_b64_e32 v[68:69], v[2:3]
	v_mov_b64_e32 v[70:71], v[2:3]
	v_mov_b64_e32 v[72:73], v[2:3]
	v_mov_b64_e32 v[74:75], v[2:3]
	v_mov_b64_e32 v[76:77], v[2:3]
	v_mov_b64_e32 v[78:79], v[2:3]
	v_mov_b64_e32 v[80:81], v[2:3]
	v_mov_b64_e32 v[82:83], v[2:3]
	v_mov_b64_e32 v[84:85], v[2:3]
	v_mov_b64_e32 v[86:87], v[2:3]
	v_mov_b64_e32 v[88:89], v[2:3]
	v_mov_b64_e32 v[90:91], v[2:3]
	v_mov_b64_e32 v[92:93], v[2:3]
	v_mov_b64_e32 v[94:95], v[2:3]
	v_mov_b64_e32 v[96:97], v[2:3]
	v_mov_b64_e32 v[98:99], v[2:3]
	v_mov_b64_e32 v[100:101], v[2:3]
	v_mov_b64_e32 v[102:103], v[2:3]
	v_mov_b64_e32 v[104:105], v[2:3]
	v_mov_b64_e32 v[106:107], v[2:3]
	v_mov_b64_e32 v[108:109], v[2:3]
	v_mov_b64_e32 v[110:111], v[2:3]
	v_mov_b64_e32 v[112:113], v[2:3]
	v_mov_b64_e32 v[114:115], v[2:3]
	v_mov_b64_e32 v[116:117], v[2:3]
	v_mov_b64_e32 v[118:119], v[2:3]
	v_mov_b64_e32 v[120:121], v[2:3]
	v_mov_b64_e32 v[122:123], v[2:3]
	v_mov_b64_e32 v[124:125], v[2:3]
	v_mov_b64_e32 v[126:127], v[2:3]
	v_mov_b64_e32 v[128:129], v[2:3]

; template <class Epi, class Sched, bool ALIGN_EPI = false, bool SP2 = false>
; __device__ __forceinline__ void gemm_phase(PG8_LAS unsigned char* lds, const Gemm g, const Sched& S, const Epi& E) {
;     ...
; #pragma unroll
;         for (int a = 0; a < 2; ++a)
; #pragma unroll
;             for (int b = 0; b < 2; ++b)
; #pragma unroll
;                 for (int m = 0; m < 4; ++m)
; #pragma unroll
;                     for (int n = 0; n < 2; ++n) acc[a][b][m][n] = (f32x4){0.f, 0.f, 0.f, 0.f};
;         cur = nxt; cA = nA; cB = nB; ++ui;
.LBB0_416:
	s_and_b64 s[28:29], s[30:31], exec
	s_cselect_b32 s28, s74, s34
	s_ashr_i32 s29, s28, 31
	s_lshl_b64 s[28:29], s[28:29], 17
	s_add_u32 s28, s39, s28
	s_addc_u32 s29, s50, s29
	s_and_b64 s[34:35], s[30:31], exec
	v_mov_b32_e32 v2, 0
	s_cselect_b32 s76, s29, s13
	s_cselect_b32 s77, s28, s12
	s_mov_b64 s[40:41], 0
	s_mov_b64 s[34:35], -1
	s_mov_b64 s[36:37], 0
	v_mov_b32_e32 v3, v2
	v_mov_b64_e32 v[4:5], v[2:3]
	v_mov_b64_e32 v[6:7], v[2:3]
	v_mov_b64_e32 v[8:9], v[2:3]
	v_mov_b64_e32 v[10:11], v[2:3]
	v_mov_b64_e32 v[12:13], v[2:3]
	v_mov_b64_e32 v[14:15], v[2:3]
	v_mov_b64_e32 v[16:17], v[2:3]
	v_mov_b64_e32 v[18:19], v[2:3]
	v_mov_b64_e32 v[20:21], v[2:3]
	v_mov_b64_e32 v[22:23], v[2:3]
	v_mov_b64_e32 v[24:25], v[2:3]
	v_mov_b64_e32 v[26:27], v[2:3]
	v_mov_b64_e32 v[28:29], v[2:3]
	v_mov_b64_e32 v[30:31], v[2:3]
	v_mov_b64_e32 v[32:33], v[2:3]
	v_mov_b64_e32 v[34:35], v[2:3]
	v_mov_b64_e32 v[36:37], v[2:3]
	v_mov_b64_e32 v[38:39], v[2:3]
	v_mov_b64_e32 v[40:41], v[2:3]
	v_mov_b64_e32 v[42:43], v[2:3]
	v_mov_b64_e32 v[44:45], v[2:3]
	v_mov_b64_e32 v[46:47], v[2:3]
	v_mov_b64_e32 v[48:49], v[2:3]
	v_mov_b64_e32 v[50:51], v[2:3]
	v_mov_b64_e32 v[52:53], v[2:3]
	v_mov_b64_e32 v[54:55], v[2:3]
	v_mov_b64_e32 v[56:57], v[2:3]
	v_mov_b64_e32 v[58:59], v[2:3]
	v_mov_b64_e32 v[60:61], v[2:3]
	v_mov_b64_e32 v[62:63], v[2:3]
	v_mov_b64_e32 v[64:65], v[2:3]
	v_mov_b64_e32 v[66:67], v[2:3]
	v_mov_b64_e32 v[68:69], v[2:3]
	v_mov_b64_e32 v[70:71], v[2:3]
	v_mov_b64_e32 v[72:73], v[2:3]
	v_mov_b64_e32 v[74:75], v[2:3]
	v_mov_b64_e32 v[76:77], v[2:3]
	v_mov_b64_e32 v[78:79], v[2:3]
	v_mov_b64_e32 v[80:81], v[2:3]
	v_mov_b64_e32 v[82:83], v[2:3]
	v_mov_b64_e32 v[84:85], v[2:3]
	v_mov_b64_e32 v[86:87], v[2:3]
	v_mov_b64_e32 v[88:89], v[2:3]
	v_mov_b64_e32 v[90:91], v[2:3]
	v_mov_b64_e32 v[92:93], v[2:3]
	v_mov_b64_e32 v[94:95], v[2:3]
	v_mov_b64_e32 v[96:97], v[2:3]
	v_mov_b64_e32 v[98:99], v[2:3]
	v_mov_b64_e32 v[100:101], v[2:3]
	v_mov_b64_e32 v[102:103], v[2:3]
	v_mov_b64_e32 v[104:105], v[2:3]
	v_mov_b64_e32 v[106:107], v[2:3]
	v_mov_b64_e32 v[108:109], v[2:3]
	v_mov_b64_e32 v[110:111], v[2:3]
	v_mov_b64_e32 v[112:113], v[2:3]
	v_mov_b64_e32 v[114:115], v[2:3]
	v_mov_b64_e32 v[116:117], v[2:3]
	v_mov_b64_e32 v[118:119], v[2:3]
	v_mov_b64_e32 v[120:121], v[2:3]
	v_mov_b64_e32 v[122:123], v[2:3]
	v_mov_b64_e32 v[124:125], v[2:3]
	v_mov_b64_e32 v[126:127], v[2:3]
	v_mov_b64_e32 v[128:129], v[2:3]

; template <class Epi, class Sched, bool ALIGN_EPI = false, bool SP2 = false>
; __device__ __forceinline__ void gemm_phase(PG8_LAS unsigned char* lds, const Gemm g, const Sched& S, const Epi& E) {
;     ...
; #pragma unroll
;         for (int a = 0; a < 2; ++a)
; #pragma unroll
;             for (int b = 0; b < 2; ++b)
; #pragma unroll
;                 for (int m = 0; m < 4; ++m)
; #pragma unroll
;                     for (int n = 0; n < 2; ++n) acc[a][b][m][n] = (f32x4){0.f, 0.f, 0.f, 0.f};
;         cur = nxt; cA = nA; cB = nB; ++ui;
.LBB0_685:
	s_add_u32 s38, s22, 0x100
	v_mov_b32_e32 v2, 0
	s_addc_u32 s39, s23, 0
	s_mov_b32 s61, -2
	v_mov_b32_e32 v3, v2
	v_mov_b64_e32 v[4:5], v[2:3]
	v_mov_b64_e32 v[6:7], v[2:3]
	v_mov_b64_e32 v[8:9], v[2:3]
	v_mov_b64_e32 v[10:11], v[2:3]
	v_mov_b64_e32 v[12:13], v[2:3]
	v_mov_b64_e32 v[14:15], v[2:3]
	v_mov_b64_e32 v[16:17], v[2:3]
	v_mov_b64_e32 v[18:19], v[2:3]
	v_mov_b64_e32 v[20:21], v[2:3]
	v_mov_b64_e32 v[22:23], v[2:3]
	v_mov_b64_e32 v[24:25], v[2:3]
	v_mov_b64_e32 v[26:27], v[2:3]
	v_mov_b64_e32 v[28:29], v[2:3]
	v_mov_b64_e32 v[30:31], v[2:3]
	v_mov_b64_e32 v[32:33], v[2:3]
	v_mov_b64_e32 v[34:35], v[2:3]
	v_mov_b64_e32 v[36:37], v[2:3]
	v_mov_b64_e32 v[38:39], v[2:3]
	v_mov_b64_e32 v[40:41], v[2:3]
	v_mov_b64_e32 v[42:43], v[2:3]
	v_mov_b64_e32 v[44:45], v[2:3]
	v_mov_b64_e32 v[46:47], v[2:3]
	v_mov_b64_e32 v[48:49], v[2:3]
	v_mov_b64_e32 v[50:51], v[2:3]
	v_mov_b64_e32 v[52:53], v[2:3]
	v_mov_b64_e32 v[54:55], v[2:3]
	v_mov_b64_e32 v[56:57], v[2:3]
	v_mov_b64_e32 v[58:59], v[2:3]
	v_mov_b64_e32 v[60:61], v[2:3]
	v_mov_b64_e32 v[62:63], v[2:3]
	v_mov_b64_e32 v[64:65], v[2:3]
	v_mov_b64_e32 v[66:67], v[2:3]
	v_mov_b64_e32 v[68:69], v[2:3]
	v_mov_b64_e32 v[70:71], v[2:3]
	v_mov_b64_e32 v[72:73], v[2:3]
	v_mov_b64_e32 v[74:75], v[2:3]
	v_mov_b64_e32 v[76:77], v[2:3]
	v_mov_b64_e32 v[78:79], v[2:3]
	v_mov_b64_e32 v[80:81], v[2:3]
	v_mov_b64_e32 v[82:83], v[2:3]
	v_mov_b64_e32 v[84:85], v[2:3]
	v_mov_b64_e32 v[86:87], v[2:3]
	v_mov_b64_e32 v[88:89], v[2:3]
	v_mov_b64_e32 v[90:91], v[2:3]
	v_mov_b64_e32 v[92:93], v[2:3]
	v_mov_b64_e32 v[94:95], v[2:3]
	v_mov_b64_e32 v[96:97], v[2:3]
	v_mov_b64_e32 v[98:99], v[2:3]
	v_mov_b64_e32 v[100:101], v[2:3]
	v_mov_b64_e32 v[102:103], v[2:3]
	v_mov_b64_e32 v[104:105], v[2:3]
	v_mov_b64_e32 v[106:107], v[2:3]
	v_mov_b64_e32 v[108:109], v[2:3]
	v_mov_b64_e32 v[110:111], v[2:3]
	v_mov_b64_e32 v[112:113], v[2:3]
	v_mov_b64_e32 v[114:115], v[2:3]
	v_mov_b64_e32 v[116:117], v[2:3]
	v_mov_b64_e32 v[118:119], v[2:3]
	v_mov_b64_e32 v[120:121], v[2:3]
	v_mov_b64_e32 v[122:123], v[2:3]
	v_mov_b64_e32 v[124:125], v[2:3]
	v_mov_b64_e32 v[126:127], v[2:3]
	v_mov_b64_e32 v[128:129], v[2:3]

; template <class Epi, class Sched, bool ALIGN_EPI = false, bool SP2 = false>
; __device__ __forceinline__ void gemm_phase(PG8_LAS unsigned char* lds, const Gemm g, const Sched& S, const Epi& E) {
;     ...
; #pragma unroll
;         for (int a = 0; a < 2; ++a)
; #pragma unroll
;             for (int b = 0; b < 2; ++b)
; #pragma unroll
;                 for (int m = 0; m < 4; ++m)
; #pragma unroll
;                     for (int n = 0; n < 2; ++n) acc[a][b][m][n] = (f32x4){0.f, 0.f, 0.f, 0.f};
;         cur = nxt; cA = nA; cB = nB; ++ui;
.LBB0_850:
	s_ashr_i32 s29, s28, 31
	s_lshl_b64 s[30:31], s[28:29], 18
	s_add_u32 s30, s47, s30
	s_addc_u32 s31, s48, s31
	s_and_b64 s[34:35], s[4:5], exec
	s_cselect_b32 s29, s31, s41
	s_cselect_b32 s38, s30, s40
	s_ashr_i32 s27, s26, 31
	s_lshl_b64 s[34:35], s[26:27], 18
	s_add_u32 s34, s49, s34
	s_addc_u32 s35, s50, s35
	s_and_b64 s[44:45], s[4:5], exec
	s_cselect_b32 s27, s35, s43
	s_cselect_b32 s39, s34, s42
	s_add_u32 s40, s40, 0x20080
	s_addc_u32 s41, s41, 0
	s_add_u32 s61, s42, 0x100
	v_mov_b32_e32 v2, 0
	s_addc_u32 s62, s43, 0
	s_mov_b32 s63, -2
	v_mov_b32_e32 v3, v2
	v_mov_b64_e32 v[4:5], v[2:3]
	v_mov_b64_e32 v[6:7], v[2:3]
	v_mov_b64_e32 v[8:9], v[2:3]
	v_mov_b64_e32 v[10:11], v[2:3]
	v_mov_b64_e32 v[12:13], v[2:3]
	v_mov_b64_e32 v[14:15], v[2:3]
	v_mov_b64_e32 v[16:17], v[2:3]
	v_mov_b64_e32 v[18:19], v[2:3]
	v_mov_b64_e32 v[20:21], v[2:3]
	v_mov_b64_e32 v[22:23], v[2:3]
	v_mov_b64_e32 v[24:25], v[2:3]
	v_mov_b64_e32 v[26:27], v[2:3]
	v_mov_b64_e32 v[28:29], v[2:3]
	v_mov_b64_e32 v[30:31], v[2:3]
	v_mov_b64_e32 v[32:33], v[2:3]
	v_mov_b64_e32 v[34:35], v[2:3]
	v_mov_b64_e32 v[36:37], v[2:3]
	v_mov_b64_e32 v[38:39], v[2:3]
	v_mov_b64_e32 v[40:41], v[2:3]
	v_mov_b64_e32 v[42:43], v[2:3]
	v_mov_b64_e32 v[44:45], v[2:3]
	v_mov_b64_e32 v[46:47], v[2:3]
	v_mov_b64_e32 v[48:49], v[2:3]
	v_mov_b64_e32 v[50:51], v[2:3]
	v_mov_b64_e32 v[52:53], v[2:3]
	v_mov_b64_e32 v[54:55], v[2:3]
	v_mov_b64_e32 v[56:57], v[2:3]
	v_mov_b64_e32 v[58:59], v[2:3]
	v_mov_b64_e32 v[60:61], v[2:3]
	v_mov_b64_e32 v[62:63], v[2:3]
	v_mov_b64_e32 v[64:65], v[2:3]
	v_mov_b64_e32 v[66:67], v[2:3]
	v_mov_b64_e32 v[68:69], v[2:3]
	v_mov_b64_e32 v[70:71], v[2:3]
	v_mov_b64_e32 v[72:73], v[2:3]
	v_mov_b64_e32 v[74:75], v[2:3]
	v_mov_b64_e32 v[76:77], v[2:3]
	v_mov_b64_e32 v[78:79], v[2:3]
	v_mov_b64_e32 v[80:81], v[2:3]
	v_mov_b64_e32 v[82:83], v[2:3]
	v_mov_b64_e32 v[84:85], v[2:3]
	v_mov_b64_e32 v[86:87], v[2:3]
	v_mov_b64_e32 v[88:89], v[2:3]
	v_mov_b64_e32 v[90:91], v[2:3]
	v_mov_b64_e32 v[92:93], v[2:3]
	v_mov_b64_e32 v[94:95], v[2:3]
	v_mov_b64_e32 v[96:97], v[2:3]
	v_mov_b64_e32 v[98:99], v[2:3]
	v_mov_b64_e32 v[100:101], v[2:3]
	v_mov_b64_e32 v[102:103], v[2:3]
	v_mov_b64_e32 v[104:105], v[2:3]
	v_mov_b64_e32 v[106:107], v[2:3]
	v_mov_b64_e32 v[108:109], v[2:3]
	v_mov_b64_e32 v[110:111], v[2:3]
	v_mov_b64_e32 v[112:113], v[2:3]
	v_mov_b64_e32 v[114:115], v[2:3]
	v_mov_b64_e32 v[116:117], v[2:3]
	v_mov_b64_e32 v[118:119], v[2:3]
	v_mov_b64_e32 v[120:121], v[2:3]
	v_mov_b64_e32 v[122:123], v[2:3]
	v_mov_b64_e32 v[124:125], v[2:3]
	v_mov_b64_e32 v[126:127], v[2:3]
	v_mov_b64_e32 v[128:129], v[2:3]

; template <class Epi, class Sched, bool ALIGN_EPI = false, bool SP2 = false>
; __device__ __forceinline__ void gemm_phase(PG8_LAS unsigned char* lds, const Gemm g, const Sched& S, const Epi& E) {
;     ...
; #pragma unroll
;         for (int a = 0; a < 2; ++a)
; #pragma unroll
;             for (int b = 0; b < 2; ++b)
; #pragma unroll
;                 for (int m = 0; m < 4; ++m)
; #pragma unroll
;                     for (int n = 0; n < 2; ++n) acc[a][b][m][n] = (f32x4){0.f, 0.f, 0.f, 0.f};
;         cur = nxt; cA = nA; cB = nB; ++ui;
.LBB0_874:
	s_ashr_i32 s25, s24, 31
	s_lshl_b64 s[26:27], s[24:25], 18
	s_add_u32 s26, s33, s26
	s_addc_u32 s27, s42, s27
	s_and_b64 s[28:29], s[4:5], exec
	s_cselect_b32 s25, s27, s35
	s_cselect_b32 s39, s26, s34
	s_ashr_i32 s23, s22, 31
	s_lshl_b64 s[28:29], s[22:23], 18
	s_add_u32 s28, s43, s28
	s_addc_u32 s29, s44, s29
	s_and_b64 s[40:41], s[4:5], exec
	s_cselect_b32 s23, s29, s37
	s_cselect_b32 s55, s28, s36
	s_add_u32 s34, s34, 0x20080
	s_addc_u32 s35, s35, 0
	s_add_u32 s56, s36, 0x100
	v_mov_b32_e32 v2, 0
	s_addc_u32 s57, s37, 0
	s_mov_b32 s58, -2
	v_mov_b32_e32 v3, v2
	v_mov_b64_e32 v[4:5], v[2:3]
	v_mov_b64_e32 v[6:7], v[2:3]
	v_mov_b64_e32 v[8:9], v[2:3]
	v_mov_b64_e32 v[10:11], v[2:3]
	v_mov_b64_e32 v[12:13], v[2:3]
	v_mov_b64_e32 v[14:15], v[2:3]
	v_mov_b64_e32 v[16:17], v[2:3]
	v_mov_b64_e32 v[18:19], v[2:3]
	v_mov_b64_e32 v[20:21], v[2:3]
	v_mov_b64_e32 v[22:23], v[2:3]
	v_mov_b64_e32 v[24:25], v[2:3]
	v_mov_b64_e32 v[26:27], v[2:3]
	v_mov_b64_e32 v[28:29], v[2:3]
	v_mov_b64_e32 v[30:31], v[2:3]
	v_mov_b64_e32 v[32:33], v[2:3]
	v_mov_b64_e32 v[34:35], v[2:3]
	v_mov_b64_e32 v[36:37], v[2:3]
	v_mov_b64_e32 v[38:39], v[2:3]
	v_mov_b64_e32 v[40:41], v[2:3]
	v_mov_b64_e32 v[42:43], v[2:3]
	v_mov_b64_e32 v[44:45], v[2:3]
	v_mov_b64_e32 v[46:47], v[2:3]
	v_mov_b64_e32 v[48:49], v[2:3]
	v_mov_b64_e32 v[50:51], v[2:3]
	v_mov_b64_e32 v[52:53], v[2:3]
	v_mov_b64_e32 v[54:55], v[2:3]
	v_mov_b64_e32 v[56:57], v[2:3]
	v_mov_b64_e32 v[58:59], v[2:3]
	v_mov_b64_e32 v[60:61], v[2:3]
	v_mov_b64_e32 v[62:63], v[2:3]
	v_mov_b64_e32 v[64:65], v[2:3]
	v_mov_b64_e32 v[66:67], v[2:3]
	v_mov_b64_e32 v[68:69], v[2:3]
	v_mov_b64_e32 v[70:71], v[2:3]
	v_mov_b64_e32 v[72:73], v[2:3]
	v_mov_b64_e32 v[74:75], v[2:3]
	v_mov_b64_e32 v[76:77], v[2:3]
	v_mov_b64_e32 v[78:79], v[2:3]
	v_mov_b64_e32 v[80:81], v[2:3]
	v_mov_b64_e32 v[82:83], v[2:3]
	v_mov_b64_e32 v[84:85], v[2:3]
	v_mov_b64_e32 v[86:87], v[2:3]
	v_mov_b64_e32 v[88:89], v[2:3]
	v_mov_b64_e32 v[90:91], v[2:3]
	v_mov_b64_e32 v[92:93], v[2:3]
	v_mov_b64_e32 v[94:95], v[2:3]
	v_mov_b64_e32 v[96:97], v[2:3]
	v_mov_b64_e32 v[98:99], v[2:3]
	v_mov_b64_e32 v[100:101], v[2:3]
	v_mov_b64_e32 v[102:103], v[2:3]
	v_mov_b64_e32 v[104:105], v[2:3]
	v_mov_b64_e32 v[106:107], v[2:3]
	v_mov_b64_e32 v[108:109], v[2:3]
	v_mov_b64_e32 v[110:111], v[2:3]
	v_mov_b64_e32 v[112:113], v[2:3]
	v_mov_b64_e32 v[114:115], v[2:3]
	v_mov_b64_e32 v[116:117], v[2:3]
	v_mov_b64_e32 v[118:119], v[2:3]
	v_mov_b64_e32 v[120:121], v[2:3]
	v_mov_b64_e32 v[122:123], v[2:3]
	v_mov_b64_e32 v[124:125], v[2:3]
	v_mov_b64_e32 v[126:127], v[2:3]
	v_mov_b64_e32 v[128:129], v[2:3]

; template <class Epi, class Sched, bool ALIGN_EPI = false, bool SP2 = false>
; __device__ __forceinline__ void gemm_phase(PG8_LAS unsigned char* lds, const Gemm g, const Sched& S, const Epi& E) {
;     ...
; #pragma unroll
;         for (int a = 0; a < 2; ++a)
; #pragma unroll
;             for (int b = 0; b < 2; ++b)
; #pragma unroll
;                 for (int m = 0; m < 4; ++m)
; #pragma unroll
;                     for (int n = 0; n < 2; ++n) acc[a][b][m][n] = (f32x4){0.f, 0.f, 0.f, 0.f};
;         cur = nxt; cA = nA; cB = nB; ++ui;
.LBB0_975:
	s_ashr_i32 s27, s26, 31
	s_lshl_b64 s[28:29], s[26:27], 18
	s_add_u32 s28, s33, s28
	s_addc_u32 s29, s44, s29
	s_and_b64 s[30:31], s[4:5], exec
	s_cselect_b32 s27, s29, s37
	s_cselect_b32 s39, s28, s36
	s_ashr_i32 s25, s24, 31
	s_lshl_b64 s[30:31], s[24:25], 18
	s_add_u32 s30, s45, s30
	s_addc_u32 s31, s46, s31
	s_and_b64 s[42:43], s[4:5], exec
	s_cselect_b32 s25, s31, s41
	s_cselect_b32 s57, s30, s40
	s_add_u32 s36, s36, 0x20080
	s_addc_u32 s37, s37, 0
	s_add_u32 s58, s40, 0x100
	v_mov_b32_e32 v2, 0
	s_addc_u32 s59, s41, 0
	s_mov_b32 s60, -2
	v_mov_b32_e32 v3, v2
	v_mov_b64_e32 v[4:5], v[2:3]
	v_mov_b64_e32 v[6:7], v[2:3]
	v_mov_b64_e32 v[8:9], v[2:3]
	v_mov_b64_e32 v[10:11], v[2:3]
	v_mov_b64_e32 v[12:13], v[2:3]
	v_mov_b64_e32 v[14:15], v[2:3]
	v_mov_b64_e32 v[16:17], v[2:3]
	v_mov_b64_e32 v[18:19], v[2:3]
	v_mov_b64_e32 v[20:21], v[2:3]
	v_mov_b64_e32 v[22:23], v[2:3]
	v_mov_b64_e32 v[24:25], v[2:3]
	v_mov_b64_e32 v[26:27], v[2:3]
	v_mov_b64_e32 v[28:29], v[2:3]
	v_mov_b64_e32 v[30:31], v[2:3]
	v_mov_b64_e32 v[32:33], v[2:3]
	v_mov_b64_e32 v[34:35], v[2:3]
	v_mov_b64_e32 v[36:37], v[2:3]
	v_mov_b64_e32 v[38:39], v[2:3]
	v_mov_b64_e32 v[40:41], v[2:3]
	v_mov_b64_e32 v[42:43], v[2:3]
	v_mov_b64_e32 v[44:45], v[2:3]
	v_mov_b64_e32 v[46:47], v[2:3]
	v_mov_b64_e32 v[48:49], v[2:3]
	v_mov_b64_e32 v[50:51], v[2:3]
	v_mov_b64_e32 v[52:53], v[2:3]
	v_mov_b64_e32 v[54:55], v[2:3]
	v_mov_b64_e32 v[56:57], v[2:3]
	v_mov_b64_e32 v[58:59], v[2:3]
	v_mov_b64_e32 v[60:61], v[2:3]
	v_mov_b64_e32 v[62:63], v[2:3]
	v_mov_b64_e32 v[64:65], v[2:3]
	v_mov_b64_e32 v[66:67], v[2:3]
	v_mov_b64_e32 v[68:69], v[2:3]
	v_mov_b64_e32 v[70:71], v[2:3]
	v_mov_b64_e32 v[72:73], v[2:3]
	v_mov_b64_e32 v[74:75], v[2:3]
	v_mov_b64_e32 v[76:77], v[2:3]
	v_mov_b64_e32 v[78:79], v[2:3]
	v_mov_b64_e32 v[80:81], v[2:3]
	v_mov_b64_e32 v[82:83], v[2:3]
	v_mov_b64_e32 v[84:85], v[2:3]
	v_mov_b64_e32 v[86:87], v[2:3]
	v_mov_b64_e32 v[88:89], v[2:3]
	v_mov_b64_e32 v[90:91], v[2:3]
	v_mov_b64_e32 v[92:93], v[2:3]
	v_mov_b64_e32 v[94:95], v[2:3]
	v_mov_b64_e32 v[96:97], v[2:3]
	v_mov_b64_e32 v[98:99], v[2:3]
	v_mov_b64_e32 v[100:101], v[2:3]
	v_mov_b64_e32 v[102:103], v[2:3]
	v_mov_b64_e32 v[104:105], v[2:3]
	v_mov_b64_e32 v[106:107], v[2:3]
	v_mov_b64_e32 v[108:109], v[2:3]
	v_mov_b64_e32 v[110:111], v[2:3]
	v_mov_b64_e32 v[112:113], v[2:3]
	v_mov_b64_e32 v[114:115], v[2:3]
	v_mov_b64_e32 v[116:117], v[2:3]
	v_mov_b64_e32 v[118:119], v[2:3]
	v_mov_b64_e32 v[120:121], v[2:3]
	v_mov_b64_e32 v[122:123], v[2:3]
	v_mov_b64_e32 v[124:125], v[2:3]
	v_mov_b64_e32 v[126:127], v[2:3]
	v_mov_b64_e32 v[128:129], v[2:3]

; template <class Epi, class Sched, bool ALIGN_EPI = false, bool SP2 = false>
; __device__ __forceinline__ void gemm_phase(PG8_LAS unsigned char* lds, const Gemm g, const Sched& S, const Epi& E) {
;     ...
; #pragma unroll
;         for (int a = 0; a < 2; ++a)
; #pragma unroll
;             for (int b = 0; b < 2; ++b)
; #pragma unroll
;                 for (int m = 0; m < 4; ++m)
; #pragma unroll
;                     for (int n = 0; n < 2; ++n) acc[a][b][m][n] = (f32x4){0.f, 0.f, 0.f, 0.f};
;         cur = nxt; cA = nA; cB = nB; ++ui;
.LBB0_1080:
	s_ashr_i32 s25, s24, 31
	s_lshl_b64 s[26:27], s[24:25], 19
	s_add_u32 s26, s33, s26
	s_addc_u32 s27, s44, s27
	s_and_b64 s[28:29], s[6:7], exec
	s_cselect_b32 s25, s27, s37
	s_cselect_b32 s31, s26, s36
	s_ashr_i32 s23, s22, 31
	s_lshl_b64 s[28:29], s[22:23], 19
	s_add_u32 s28, s45, s28
	s_addc_u32 s29, s46, s29
	s_and_b64 s[38:39], s[6:7], exec
	s_cselect_b32 s23, s29, s41
	s_cselect_b32 s38, s28, s40
	s_add_u32 s36, s36, 0x40080
	s_addc_u32 s37, s37, 0
	s_add_u32 s39, s40, 0x100
	v_mov_b32_e32 v2, 0
	s_addc_u32 s58, s41, 0
	s_mov_b32 s59, -2
	s_waitcnt lgkmcnt(0)
	v_mov_b32_e32 v3, v2
	v_mov_b64_e32 v[4:5], v[2:3]
	v_mov_b64_e32 v[6:7], v[2:3]
	v_mov_b64_e32 v[8:9], v[2:3]
	v_mov_b64_e32 v[10:11], v[2:3]
	v_mov_b64_e32 v[12:13], v[2:3]
	v_mov_b64_e32 v[14:15], v[2:3]
	v_mov_b64_e32 v[16:17], v[2:3]
	v_mov_b64_e32 v[18:19], v[2:3]
	v_mov_b64_e32 v[20:21], v[2:3]
	v_mov_b64_e32 v[22:23], v[2:3]
	v_mov_b64_e32 v[24:25], v[2:3]
	v_mov_b64_e32 v[26:27], v[2:3]
	v_mov_b64_e32 v[28:29], v[2:3]
	v_mov_b64_e32 v[30:31], v[2:3]
	v_mov_b64_e32 v[32:33], v[2:3]
	v_mov_b64_e32 v[34:35], v[2:3]
	v_mov_b64_e32 v[36:37], v[2:3]
	v_mov_b64_e32 v[38:39], v[2:3]
	v_mov_b64_e32 v[40:41], v[2:3]
	v_mov_b64_e32 v[42:43], v[2:3]
	v_mov_b64_e32 v[44:45], v[2:3]
	v_mov_b64_e32 v[46:47], v[2:3]
	v_mov_b64_e32 v[48:49], v[2:3]
	v_mov_b64_e32 v[50:51], v[2:3]
	v_mov_b64_e32 v[52:53], v[2:3]
	v_mov_b64_e32 v[54:55], v[2:3]
	v_mov_b64_e32 v[56:57], v[2:3]
	v_mov_b64_e32 v[58:59], v[2:3]
	v_mov_b64_e32 v[60:61], v[2:3]
	v_mov_b64_e32 v[62:63], v[2:3]
	v_mov_b64_e32 v[64:65], v[2:3]
	v_mov_b64_e32 v[66:67], v[2:3]
	v_mov_b64_e32 v[68:69], v[2:3]
	v_mov_b64_e32 v[70:71], v[2:3]
	v_mov_b64_e32 v[72:73], v[2:3]
	v_mov_b64_e32 v[74:75], v[2:3]
	v_mov_b64_e32 v[76:77], v[2:3]
	v_mov_b64_e32 v[78:79], v[2:3]
	v_mov_b64_e32 v[80:81], v[2:3]
	v_mov_b64_e32 v[82:83], v[2:3]
	v_mov_b64_e32 v[84:85], v[2:3]
	v_mov_b64_e32 v[86:87], v[2:3]
	v_mov_b64_e32 v[88:89], v[2:3]
	v_mov_b64_e32 v[90:91], v[2:3]
	v_mov_b64_e32 v[92:93], v[2:3]
	v_mov_b64_e32 v[94:95], v[2:3]
	v_mov_b64_e32 v[96:97], v[2:3]
	v_mov_b64_e32 v[98:99], v[2:3]
	v_mov_b64_e32 v[100:101], v[2:3]
	v_mov_b64_e32 v[102:103], v[2:3]
	v_mov_b64_e32 v[104:105], v[2:3]
	v_mov_b64_e32 v[106:107], v[2:3]
	v_mov_b64_e32 v[108:109], v[2:3]
	v_mov_b64_e32 v[110:111], v[2:3]
	v_mov_b64_e32 v[112:113], v[2:3]
	v_mov_b64_e32 v[114:115], v[2:3]
	v_mov_b64_e32 v[116:117], v[2:3]
	v_mov_b64_e32 v[118:119], v[2:3]
	v_mov_b64_e32 v[120:121], v[2:3]
	v_mov_b64_e32 v[122:123], v[2:3]
	v_mov_b64_e32 v[124:125], v[2:3]
	v_mov_b64_e32 v[126:127], v[2:3]
	v_mov_b64_e32 v[128:129], v[2:3]

; template <class Epi, class Sched, bool ALIGN_EPI = false, bool SP2 = false>
; __device__ __forceinline__ void gemm_phase(PG8_LAS unsigned char* lds, const Gemm g, const Sched& S, const Epi& E) {
;     ...
; #pragma unroll
;         for (int a = 0; a < 2; ++a)
; #pragma unroll
;             for (int b = 0; b < 2; ++b)
; #pragma unroll
;                 for (int m = 0; m < 4; ++m)
; #pragma unroll
;                     for (int n = 0; n < 2; ++n) acc[a][b][m][n] = (f32x4){0.f, 0.f, 0.f, 0.f};
;         cur = nxt; cA = nA; cB = nB; ++ui;
.LBB0_1191:
	s_ashr_i32 s49, s48, 31
	s_lshl_b64 s[38:39], s[48:49], 19
	s_add_u32 s50, s66, s38
	s_addc_u32 s51, s67, s39
	s_and_b64 s[38:39], s[12:13], exec
	s_cselect_b32 s33, s51, s59
	s_cselect_b32 s38, s50, s58
	s_ashr_i32 s47, s46, 31
	s_lshl_b64 s[52:53], s[46:47], 19
	s_add_u32 s52, s68, s52
	s_addc_u32 s53, s69, s53
	s_and_b64 s[62:63], s[12:13], exec
	s_cselect_b32 s39, s53, s61
	s_cselect_b32 s47, s52, s60
	s_add_u32 s49, s60, 0x100
	v_mov_b32_e32 v0, 0
	s_addc_u32 s55, s61, 0
	s_mov_b32 s57, -2
	v_mov_b32_e32 v1, v0
	v_mov_b64_e32 v[2:3], v[0:1]
	v_mov_b64_e32 v[4:5], v[0:1]
	v_mov_b64_e32 v[6:7], v[0:1]
	v_mov_b64_e32 v[8:9], v[0:1]
	v_mov_b64_e32 v[10:11], v[0:1]
	v_mov_b64_e32 v[12:13], v[0:1]
	v_mov_b64_e32 v[14:15], v[0:1]
	v_mov_b64_e32 v[16:17], v[0:1]
	v_mov_b64_e32 v[18:19], v[0:1]
	v_mov_b64_e32 v[20:21], v[0:1]
	v_mov_b64_e32 v[22:23], v[0:1]
	v_mov_b64_e32 v[24:25], v[0:1]
	v_mov_b64_e32 v[26:27], v[0:1]
	v_mov_b64_e32 v[28:29], v[0:1]
	v_mov_b64_e32 v[30:31], v[0:1]
	v_mov_b64_e32 v[32:33], v[0:1]
	v_mov_b64_e32 v[34:35], v[0:1]
	v_mov_b64_e32 v[36:37], v[0:1]
	v_mov_b64_e32 v[38:39], v[0:1]
	v_mov_b64_e32 v[40:41], v[0:1]
	v_mov_b64_e32 v[42:43], v[0:1]
	v_mov_b64_e32 v[44:45], v[0:1]
	v_mov_b64_e32 v[46:47], v[0:1]
	v_mov_b64_e32 v[48:49], v[0:1]
	v_mov_b64_e32 v[50:51], v[0:1]
	v_mov_b64_e32 v[52:53], v[0:1]
	v_mov_b64_e32 v[54:55], v[0:1]
	v_mov_b64_e32 v[56:57], v[0:1]
	v_mov_b64_e32 v[58:59], v[0:1]
	v_mov_b64_e32 v[68:69], v[0:1]
	v_mov_b64_e32 v[70:71], v[0:1]
	v_mov_b64_e32 v[96:97], v[0:1]
	v_mov_b64_e32 v[98:99], v[0:1]
	v_mov_b64_e32 v[100:101], v[0:1]
	v_mov_b64_e32 v[102:103], v[0:1]
	v_mov_b64_e32 v[104:105], v[0:1]
	v_mov_b64_e32 v[106:107], v[0:1]
	v_mov_b64_e32 v[108:109], v[0:1]
	v_mov_b64_e32 v[110:111], v[0:1]
	v_mov_b64_e32 v[116:117], v[0:1]
	v_mov_b64_e32 v[118:119], v[0:1]
	v_mov_b64_e32 v[120:121], v[0:1]
	v_mov_b64_e32 v[122:123], v[0:1]
	v_mov_b64_e32 v[124:125], v[0:1]
	v_mov_b64_e32 v[126:127], v[0:1]
	v_mov_b64_e32 v[128:129], v[0:1]
	v_mov_b64_e32 v[130:131], v[0:1]
	v_mov_b64_e32 v[132:133], v[0:1]
	v_mov_b64_e32 v[134:135], v[0:1]
	v_mov_b64_e32 v[136:137], v[0:1]
	v_mov_b64_e32 v[138:139], v[0:1]
	v_mov_b64_e32 v[144:145], v[0:1]
	v_mov_b64_e32 v[146:147], v[0:1]
	v_mov_b64_e32 v[150:151], v[0:1]
	v_mov_b64_e32 v[152:153], v[0:1]
	v_mov_b64_e32 v[154:155], v[0:1]
	v_mov_b64_e32 v[156:157], v[0:1]
	v_mov_b64_e32 v[158:159], v[0:1]
	v_mov_b64_e32 v[160:161], v[0:1]
	v_mov_b64_e32 v[162:163], v[0:1]
	v_mov_b64_e32 v[164:165], v[0:1]
	v_mov_b64_e32 v[166:167], v[0:1]
	v_mov_b64_e32 v[168:169], v[0:1]

; template <class Epi, class Sched, bool ALIGN_EPI = false, bool SP2 = false>
; __device__ __forceinline__ void gemm_phase(PG8_LAS unsigned char* lds, const Gemm g, const Sched& S, const Epi& E) {
;     ...
; #pragma unroll
;         for (int a = 0; a < 2; ++a)
; #pragma unroll
;             for (int b = 0; b < 2; ++b)
; #pragma unroll
;                 for (int m = 0; m < 4; ++m)
; #pragma unroll
;                     for (int n = 0; n < 2; ++n) acc[a][b][m][n] = (f32x4){0.f, 0.f, 0.f, 0.f};
;         cur = nxt; cA = nA; cB = nB; ++ui;
.LBB0_1328:
	s_add_u32 s47, s20, 0x100
	v_mov_b32_e32 v0, 0
	s_addc_u32 s48, s21, 0
	s_mov_b32 s49, -2
	v_mov_b32_e32 v1, v0
	v_mov_b64_e32 v[2:3], v[0:1]
	v_mov_b64_e32 v[4:5], v[0:1]
	v_mov_b64_e32 v[6:7], v[0:1]
	v_mov_b64_e32 v[8:9], v[0:1]
	v_mov_b64_e32 v[10:11], v[0:1]
	v_mov_b64_e32 v[12:13], v[0:1]
	v_mov_b64_e32 v[14:15], v[0:1]
	v_mov_b64_e32 v[16:17], v[0:1]
	v_mov_b64_e32 v[18:19], v[0:1]
	v_mov_b64_e32 v[20:21], v[0:1]
	v_mov_b64_e32 v[22:23], v[0:1]
	v_mov_b64_e32 v[24:25], v[0:1]
	v_mov_b64_e32 v[26:27], v[0:1]
	v_mov_b64_e32 v[28:29], v[0:1]
	v_mov_b64_e32 v[30:31], v[0:1]
	v_mov_b64_e32 v[32:33], v[0:1]
	v_mov_b64_e32 v[34:35], v[0:1]
	v_mov_b64_e32 v[36:37], v[0:1]
	v_mov_b64_e32 v[38:39], v[0:1]
	v_mov_b64_e32 v[40:41], v[0:1]
	v_mov_b64_e32 v[42:43], v[0:1]
	v_mov_b64_e32 v[44:45], v[0:1]
	v_mov_b64_e32 v[46:47], v[0:1]
	v_mov_b64_e32 v[48:49], v[0:1]
	v_mov_b64_e32 v[50:51], v[0:1]
	v_mov_b64_e32 v[52:53], v[0:1]
	v_mov_b64_e32 v[54:55], v[0:1]
	v_mov_b64_e32 v[56:57], v[0:1]
	v_mov_b64_e32 v[58:59], v[0:1]
	v_mov_b64_e32 v[60:61], v[0:1]
	v_mov_b64_e32 v[62:63], v[0:1]
	v_mov_b64_e32 v[64:65], v[0:1]
	v_mov_b64_e32 v[66:67], v[0:1]
	v_mov_b64_e32 v[68:69], v[0:1]
	v_mov_b64_e32 v[70:71], v[0:1]
	v_mov_b64_e32 v[72:73], v[0:1]
	v_mov_b64_e32 v[74:75], v[0:1]
	v_mov_b64_e32 v[76:77], v[0:1]
	v_mov_b64_e32 v[78:79], v[0:1]
	v_mov_b64_e32 v[80:81], v[0:1]
	v_mov_b64_e32 v[82:83], v[0:1]
	v_mov_b64_e32 v[84:85], v[0:1]
	v_mov_b64_e32 v[86:87], v[0:1]
	v_mov_b64_e32 v[88:89], v[0:1]
	v_mov_b64_e32 v[90:91], v[0:1]
	v_mov_b64_e32 v[92:93], v[0:1]
	v_mov_b64_e32 v[94:95], v[0:1]
	v_mov_b64_e32 v[96:97], v[0:1]
	v_mov_b64_e32 v[98:99], v[0:1]
	v_mov_b64_e32 v[100:101], v[0:1]
	v_mov_b64_e32 v[102:103], v[0:1]
	v_mov_b64_e32 v[104:105], v[0:1]
	v_mov_b64_e32 v[106:107], v[0:1]
	v_mov_b64_e32 v[108:109], v[0:1]
	v_mov_b64_e32 v[110:111], v[0:1]
	v_mov_b64_e32 v[112:113], v[0:1]
	v_mov_b64_e32 v[114:115], v[0:1]
	v_mov_b64_e32 v[116:117], v[0:1]
	v_mov_b64_e32 v[118:119], v[0:1]
	v_mov_b64_e32 v[120:121], v[0:1]
	v_mov_b64_e32 v[122:123], v[0:1]
	v_mov_b64_e32 v[124:125], v[0:1]
	v_mov_b64_e32 v[126:127], v[0:1]
